# skinny FFN-out split-K loops: all 32 loads of an iteration issued up front, 128B line halves adjacent
# speedup vs baseline: 1.0105x; 1.0059x over previous
; #define SK_MMA(A_, B_) do { _Pragma("unroll") for (int kk = 0; kk < 2; ++kk) _Pragma("unroll") for (int bj = 0; bj < 2; ++bj) _Pragma("unroll") for (int m = 0; m < 4; ++m) _Pragma("unroll") for (int n = 0; n < 2; ++n) \
;         acc[AI][bj][m][n] = __builtin_amdgcn_mfma_f32_16x16x32_bf16(B_[kk][bj][n], A_[kk][m], acc[AI][bj][m][n], 0, 0, 0); } while (0)
; template <class Epi, int AI>
; __device__ __forceinline__ void skinny_item(LAS unsigned char* lds, const Gemm g, const Epi& E, const Unit u, int wr, int wc, int wave, int lane) {
;     ...
;     const int nch = g.K >> 7, kbeg = ((wave * nch) >> 3) << 7, kend = (((wave + 1) * nch) >> 3) << 7;
;     bf16x8 a0[2][4], b0[2][2][2], a1[2][4], b1[2][2][2];
;     ...
; #pragma unroll 1
;     for (int k = kbeg; k < kend; k += 128) {
;         SK_LOAD(a0, b0, k);
;         SK_LOAD(a1, b1, k + 64);
;         SK_MMA(a0, b0);
;         SK_MMA(a1, b1);
;     }
.LBB0_1326:
	v_lshl_add_u64 v[100:101], v[88:89], 0, s[10:11]
	v_add_co_u32_e32 v182, vcc, s51, v100
	v_lshl_add_u64 v[102:103], v[66:67], 0, s[10:11]
	s_nop 1
	v_addc_co_u32_e32 v183, vcc, 0, v101, vcc
	v_lshl_add_u64 v[130:131], v[86:87], 0, s[10:11]
	v_add_co_u32_e32 v184, vcc, s51, v102
	v_lshl_add_u64 v[104:105], v[90:91], 0, s[10:11]
	v_lshl_add_u64 v[178:179], v[68:69], 0, s[10:11]
	v_lshl_add_u64 v[180:181], v[84:85], 0, s[10:11]
	v_addc_co_u32_e32 v185, vcc, 0, v103, vcc
	v_lshl_add_u64 v[162:163], v[70:71], 0, s[10:11]
	v_add_co_u32_e32 v186, vcc, s51, v162
	v_lshl_add_u64 v[166:167], v[64:65], 0, s[10:11]
	s_nop 1
	v_addc_co_u32_e32 v187, vcc, 0, v163, vcc
	v_add_co_u32_e32 v188, vcc, s51, v166
	s_nop 1
	v_addc_co_u32_e32 v189, vcc, 0, v167, vcc
	s_addk_i32 s20, 0x80
	s_add_u32 s10, s10, 0x100
	s_addc_u32 s11, s11, 0
	s_cmp_lt_i32 s20, s37
	global_load_dwordx4 v[100:103], v[104:105], off
	global_load_dwordx4 v[162:165], v[104:105], off offset:64
	global_load_dwordx4 v[166:169], v[182:183], off
	global_load_dwordx4 v[92:95], v[182:183], off offset:64
	global_load_dwordx4 v[96:99], v[130:131], off
	global_load_dwordx4 v[134:137], v[130:131], off offset:64
	global_load_dwordx4 v[138:141], v[178:179], off
	global_load_dwordx4 v[142:145], v[178:179], off offset:64
	global_load_dwordx4 v[146:149], v[180:181], off
	global_load_dwordx4 v[150:153], v[180:181], off offset:64
	global_load_dwordx4 v[154:157], v[184:185], off
	global_load_dwordx4 v[158:161], v[184:185], off offset:64
	global_load_dwordx4 v[170:173], v[186:187], off
	global_load_dwordx4 v[174:177], v[186:187], off offset:64
	global_load_dwordx4 v[190:193], v[188:189], off
	global_load_dwordx4 v[194:197], v[188:189], off offset:64
	global_load_dwordx4 v[198:201], v[104:105], off offset:128
	global_load_dwordx4 v[202:205], v[104:105], off offset:192
	global_load_dwordx4 v[206:209], v[182:183], off offset:128
	global_load_dwordx4 v[210:213], v[182:183], off offset:192
	global_load_dwordx4 v[214:217], v[130:131], off offset:128
	global_load_dwordx4 v[218:221], v[130:131], off offset:192
	global_load_dwordx4 v[222:225], v[178:179], off offset:128
	global_load_dwordx4 v[226:229], v[178:179], off offset:192
	global_load_dwordx4 v[230:233], v[180:181], off offset:128
	global_load_dwordx4 v[234:237], v[180:181], off offset:192
	global_load_dwordx4 v[240:243], v[184:185], off offset:128
	global_load_dwordx4 v[244:247], v[184:185], off offset:192
	global_load_dwordx4 v[248:251], v[186:187], off offset:128
	s_waitcnt vmcnt(26)
	v_mfma_f32_16x16x32_bf16 v[56:59], v[166:169], v[100:103], v[56:59]
	s_waitcnt vmcnt(24)
	v_mfma_f32_16x16x32_bf16 v[52:55], v[166:169], v[96:99], v[52:55]
	s_waitcnt vmcnt(22)
	v_mfma_f32_16x16x32_bf16 v[44:47], v[166:169], v[138:141], v[44:47]
	s_waitcnt vmcnt(20)
	v_mfma_f32_16x16x32_bf16 v[36:39], v[166:169], v[146:149], v[36:39]
	s_waitcnt vmcnt(18)
	v_mfma_f32_16x16x32_bf16 v[60:63], v[154:157], v[100:103], v[60:63]
	v_mfma_f32_16x16x32_bf16 v[48:51], v[154:157], v[96:99], v[48:51]
	v_mfma_f32_16x16x32_bf16 v[40:43], v[154:157], v[138:141], v[40:43]
	v_mfma_f32_16x16x32_bf16 v[32:35], v[154:157], v[146:149], v[32:35]
	global_load_dwordx4 v[154:157], v[186:187], off offset:192
	s_waitcnt vmcnt(17)
	v_mfma_f32_16x16x32_bf16 v[28:31], v[170:173], v[100:103], v[28:31]
	v_mfma_f32_16x16x32_bf16 v[16:19], v[170:173], v[96:99], v[16:19]
	v_mfma_f32_16x16x32_bf16 v[4:7], v[170:173], v[138:141], v[4:7]
	v_mfma_f32_16x16x32_bf16 v[0:3], v[170:173], v[146:149], v[0:3]
	global_load_dwordx4 v[170:173], v[188:189], off offset:128
	v_mfma_f32_16x16x32_bf16 v[56:59], v[92:95], v[162:165], v[56:59]
	v_mfma_f32_16x16x32_bf16 v[60:63], v[158:161], v[162:165], v[60:63]
	v_mfma_f32_16x16x32_bf16 v[52:55], v[92:95], v[134:137], v[52:55]
	v_mfma_f32_16x16x32_bf16 v[48:51], v[158:161], v[134:137], v[48:51]
	v_mfma_f32_16x16x32_bf16 v[44:47], v[92:95], v[142:145], v[44:47]
	v_mfma_f32_16x16x32_bf16 v[40:43], v[158:161], v[142:145], v[40:43]
	v_mfma_f32_16x16x32_bf16 v[36:39], v[92:95], v[150:153], v[36:39]
	global_load_dwordx4 v[92:95], v[188:189], off offset:192
	s_waitcnt vmcnt(17)
; #define SK_MMA(A_, B_) do { _Pragma("unroll") for (int kk = 0; kk < 2; ++kk) _Pragma("unroll") for (int bj = 0; bj < 2; ++bj) _Pragma("unroll") for (int m = 0; m < 4; ++m) _Pragma("unroll") for (int n = 0; n < 2; ++n) \
;         acc[AI][bj][m][n] = __builtin_amdgcn_mfma_f32_16x16x32_bf16(B_[kk][bj][n], A_[kk][m], acc[AI][bj][m][n], 0, 0, 0); } while (0)
; template <class Epi, int AI>
; __device__ __forceinline__ void skinny_item(LAS unsigned char* lds, const Gemm g, const Epi& E, const Unit u, int wr, int wc, int wave, int lane) {
;     ...
; #pragma unroll 1
;     for (int k = kbeg; k < kend; k += 128) {
;         SK_LOAD(a0, b0, k);
;         SK_LOAD(a1, b1, k + 64);
;         SK_MMA(a0, b0);
;         SK_MMA(a1, b1);
	v_mfma_f32_16x16x32_bf16 v[24:27], v[190:193], v[100:103], v[24:27]
	v_mfma_f32_16x16x32_bf16 v[20:23], v[190:193], v[96:99], v[20:23]
	v_mfma_f32_16x16x32_bf16 v[8:11], v[190:193], v[138:141], v[8:11]
	v_mfma_f32_16x16x32_bf16 v[12:15], v[190:193], v[146:149], v[12:15]
	v_mfma_f32_16x16x32_bf16 v[32:35], v[158:161], v[150:153], v[32:35]
	v_mfma_f32_16x16x32_bf16 v[28:31], v[174:177], v[162:165], v[28:31]
	s_waitcnt vmcnt(16)
	v_mfma_f32_16x16x32_bf16 v[24:27], v[194:197], v[162:165], v[24:27]
	v_mfma_f32_16x16x32_bf16 v[16:19], v[174:177], v[134:137], v[16:19]
	v_mfma_f32_16x16x32_bf16 v[20:23], v[194:197], v[134:137], v[20:23]
	v_mfma_f32_16x16x32_bf16 v[4:7], v[174:177], v[142:145], v[4:7]
	v_mfma_f32_16x16x32_bf16 v[8:11], v[194:197], v[142:145], v[8:11]
	v_mfma_f32_16x16x32_bf16 v[0:3], v[174:177], v[150:153], v[0:3]
	v_mfma_f32_16x16x32_bf16 v[12:15], v[194:197], v[150:153], v[12:15]
	s_waitcnt vmcnt(13)
	v_mfma_f32_16x16x32_bf16 v[56:59], v[206:209], v[198:201], v[56:59]
	s_waitcnt vmcnt(11)
	v_mfma_f32_16x16x32_bf16 v[52:55], v[206:209], v[214:217], v[52:55]
	s_waitcnt vmcnt(9)
	v_mfma_f32_16x16x32_bf16 v[44:47], v[206:209], v[222:225], v[44:47]
	s_waitcnt vmcnt(7)
	v_mfma_f32_16x16x32_bf16 v[36:39], v[206:209], v[230:233], v[36:39]
	s_waitcnt vmcnt(5)
	v_mfma_f32_16x16x32_bf16 v[60:63], v[240:243], v[198:201], v[60:63]
	v_mfma_f32_16x16x32_bf16 v[48:51], v[240:243], v[214:217], v[48:51]
	v_mfma_f32_16x16x32_bf16 v[40:43], v[240:243], v[222:225], v[40:43]
	v_mfma_f32_16x16x32_bf16 v[32:35], v[240:243], v[230:233], v[32:35]
	s_waitcnt vmcnt(3)
	v_mfma_f32_16x16x32_bf16 v[28:31], v[248:251], v[198:201], v[28:31]
	s_waitcnt vmcnt(1)
	v_mfma_f32_16x16x32_bf16 v[24:27], v[170:173], v[198:201], v[24:27]
	v_mfma_f32_16x16x32_bf16 v[16:19], v[248:251], v[214:217], v[16:19]
	v_mfma_f32_16x16x32_bf16 v[20:23], v[170:173], v[214:217], v[20:23]
	v_mfma_f32_16x16x32_bf16 v[4:7], v[248:251], v[222:225], v[4:7]
	v_mfma_f32_16x16x32_bf16 v[8:11], v[170:173], v[222:225], v[8:11]
	v_mfma_f32_16x16x32_bf16 v[0:3], v[248:251], v[230:233], v[0:3]
	v_mfma_f32_16x16x32_bf16 v[12:15], v[170:173], v[230:233], v[12:15]
	v_mfma_f32_16x16x32_bf16 v[56:59], v[210:213], v[202:205], v[56:59]
	v_mfma_f32_16x16x32_bf16 v[60:63], v[244:247], v[202:205], v[60:63]
	v_mfma_f32_16x16x32_bf16 v[52:55], v[210:213], v[218:221], v[52:55]
	v_mfma_f32_16x16x32_bf16 v[48:51], v[244:247], v[218:221], v[48:51]
	v_mfma_f32_16x16x32_bf16 v[44:47], v[210:213], v[226:229], v[44:47]
	v_mfma_f32_16x16x32_bf16 v[40:43], v[244:247], v[226:229], v[40:43]
	v_mfma_f32_16x16x32_bf16 v[36:39], v[210:213], v[234:237], v[36:39]
	v_mfma_f32_16x16x32_bf16 v[32:35], v[244:247], v[234:237], v[32:35]
	v_mfma_f32_16x16x32_bf16 v[28:31], v[154:157], v[202:205], v[28:31]
	s_waitcnt vmcnt(0)
	v_mfma_f32_16x16x32_bf16 v[24:27], v[92:95], v[202:205], v[24:27]
	v_mfma_f32_16x16x32_bf16 v[16:19], v[154:157], v[218:221], v[16:19]
	v_mfma_f32_16x16x32_bf16 v[20:23], v[92:95], v[218:221], v[20:23]
	v_mfma_f32_16x16x32_bf16 v[4:7], v[154:157], v[226:229], v[4:7]
	v_mfma_f32_16x16x32_bf16 v[8:11], v[92:95], v[226:229], v[8:11]
	v_mfma_f32_16x16x32_bf16 v[0:3], v[154:157], v[234:237], v[0:3]
	v_mfma_f32_16x16x32_bf16 v[12:15], v[92:95], v[234:237], v[12:15]
	s_cbranch_scc1 .LBB0_1326
	s_branch .LBB0_1328

; #define SK_MMA(A_, B_) do { _Pragma("unroll") for (int kk = 0; kk < 2; ++kk) _Pragma("unroll") for (int bj = 0; bj < 2; ++bj) _Pragma("unroll") for (int m = 0; m < 4; ++m) _Pragma("unroll") for (int n = 0; n < 2; ++n) \
;         acc[AI][bj][m][n] = __builtin_amdgcn_mfma_f32_16x16x32_bf16(B_[kk][bj][n], A_[kk][m], acc[AI][bj][m][n], 0, 0, 0); } while (0)
; template <class Epi, int AI>
; __device__ __forceinline__ void skinny_item(LAS unsigned char* lds, const Gemm g, const Epi& E, const Unit u, int wr, int wc, int wave, int lane) {
;     ...
;     const int nch = g.K >> 7, kbeg = ((wave * nch) >> 3) << 7, kend = (((wave + 1) * nch) >> 3) << 7;
;     bf16x8 a0[2][4], b0[2][2][2], a1[2][4], b1[2][2][2];
;     ...
; #pragma unroll 1
;     for (int k = kbeg; k < kend; k += 128) {
;         SK_LOAD(a0, b0, k);
;         SK_LOAD(a1, b1, k + 64);
;         SK_MMA(a0, b0);
;         SK_MMA(a1, b1);
;     }
.LBB0_1366:
	v_lshl_add_u64 v[100:101], v[88:89], 0, s[8:9]
	v_add_co_u32_e32 v182, vcc, s51, v100
	v_lshl_add_u64 v[102:103], v[66:67], 0, s[8:9]
	s_nop 1
	v_addc_co_u32_e32 v183, vcc, 0, v101, vcc
	v_lshl_add_u64 v[130:131], v[86:87], 0, s[8:9]
	v_add_co_u32_e32 v184, vcc, s51, v102
	v_lshl_add_u64 v[104:105], v[90:91], 0, s[8:9]
	v_lshl_add_u64 v[178:179], v[68:69], 0, s[8:9]
	v_lshl_add_u64 v[180:181], v[84:85], 0, s[8:9]
	v_addc_co_u32_e32 v185, vcc, 0, v103, vcc
	v_lshl_add_u64 v[162:163], v[70:71], 0, s[8:9]
	v_add_co_u32_e32 v186, vcc, s51, v162
	v_lshl_add_u64 v[166:167], v[64:65], 0, s[8:9]
	s_nop 1
	v_addc_co_u32_e32 v187, vcc, 0, v163, vcc
	v_add_co_u32_e32 v188, vcc, s51, v166
	s_nop 1
	v_addc_co_u32_e32 v189, vcc, 0, v167, vcc
	s_addk_i32 s10, 0x80
	s_add_u32 s8, s8, 0x100
	s_addc_u32 s9, s9, 0
	s_cmp_lt_i32 s10, s37
	global_load_dwordx4 v[100:103], v[104:105], off
	global_load_dwordx4 v[162:165], v[104:105], off offset:64
	global_load_dwordx4 v[166:169], v[182:183], off
	global_load_dwordx4 v[92:95], v[182:183], off offset:64
	global_load_dwordx4 v[96:99], v[130:131], off
	global_load_dwordx4 v[134:137], v[130:131], off offset:64
	global_load_dwordx4 v[138:141], v[178:179], off
	global_load_dwordx4 v[142:145], v[178:179], off offset:64
	global_load_dwordx4 v[146:149], v[180:181], off
	global_load_dwordx4 v[150:153], v[180:181], off offset:64
	global_load_dwordx4 v[154:157], v[184:185], off
	global_load_dwordx4 v[158:161], v[184:185], off offset:64
	global_load_dwordx4 v[170:173], v[186:187], off
	global_load_dwordx4 v[174:177], v[186:187], off offset:64
	global_load_dwordx4 v[190:193], v[188:189], off
	global_load_dwordx4 v[194:197], v[188:189], off offset:64
	global_load_dwordx4 v[198:201], v[104:105], off offset:128
	global_load_dwordx4 v[202:205], v[104:105], off offset:192
	global_load_dwordx4 v[206:209], v[182:183], off offset:128
	global_load_dwordx4 v[210:213], v[182:183], off offset:192
	global_load_dwordx4 v[214:217], v[130:131], off offset:128
	global_load_dwordx4 v[218:221], v[130:131], off offset:192
	global_load_dwordx4 v[222:225], v[178:179], off offset:128
	global_load_dwordx4 v[226:229], v[178:179], off offset:192
	global_load_dwordx4 v[230:233], v[180:181], off offset:128
	global_load_dwordx4 v[234:237], v[180:181], off offset:192
	global_load_dwordx4 v[240:243], v[184:185], off offset:128
	global_load_dwordx4 v[244:247], v[184:185], off offset:192
	global_load_dwordx4 v[248:251], v[186:187], off offset:128
	s_waitcnt vmcnt(26)
	v_mfma_f32_16x16x32_bf16 v[56:59], v[166:169], v[100:103], v[56:59]
	s_waitcnt vmcnt(24)
	v_mfma_f32_16x16x32_bf16 v[52:55], v[166:169], v[96:99], v[52:55]
	s_waitcnt vmcnt(22)
	v_mfma_f32_16x16x32_bf16 v[44:47], v[166:169], v[138:141], v[44:47]
	s_waitcnt vmcnt(20)
	v_mfma_f32_16x16x32_bf16 v[36:39], v[166:169], v[146:149], v[36:39]
	s_waitcnt vmcnt(18)
	v_mfma_f32_16x16x32_bf16 v[60:63], v[154:157], v[100:103], v[60:63]
	v_mfma_f32_16x16x32_bf16 v[48:51], v[154:157], v[96:99], v[48:51]
	v_mfma_f32_16x16x32_bf16 v[40:43], v[154:157], v[138:141], v[40:43]
	v_mfma_f32_16x16x32_bf16 v[32:35], v[154:157], v[146:149], v[32:35]
	global_load_dwordx4 v[154:157], v[186:187], off offset:192
	s_waitcnt vmcnt(17)
	v_mfma_f32_16x16x32_bf16 v[28:31], v[170:173], v[100:103], v[28:31]
	v_mfma_f32_16x16x32_bf16 v[16:19], v[170:173], v[96:99], v[16:19]
	v_mfma_f32_16x16x32_bf16 v[4:7], v[170:173], v[138:141], v[4:7]
	v_mfma_f32_16x16x32_bf16 v[0:3], v[170:173], v[146:149], v[0:3]
	global_load_dwordx4 v[170:173], v[188:189], off offset:128
	v_mfma_f32_16x16x32_bf16 v[56:59], v[92:95], v[162:165], v[56:59]
	v_mfma_f32_16x16x32_bf16 v[60:63], v[158:161], v[162:165], v[60:63]
	v_mfma_f32_16x16x32_bf16 v[52:55], v[92:95], v[134:137], v[52:55]
	v_mfma_f32_16x16x32_bf16 v[48:51], v[158:161], v[134:137], v[48:51]
	v_mfma_f32_16x16x32_bf16 v[44:47], v[92:95], v[142:145], v[44:47]
	v_mfma_f32_16x16x32_bf16 v[40:43], v[158:161], v[142:145], v[40:43]
	v_mfma_f32_16x16x32_bf16 v[36:39], v[92:95], v[150:153], v[36:39]
	global_load_dwordx4 v[92:95], v[188:189], off offset:192
	s_waitcnt vmcnt(17)
; #define SK_MMA(A_, B_) do { _Pragma("unroll") for (int kk = 0; kk < 2; ++kk) _Pragma("unroll") for (int bj = 0; bj < 2; ++bj) _Pragma("unroll") for (int m = 0; m < 4; ++m) _Pragma("unroll") for (int n = 0; n < 2; ++n) \
;         acc[AI][bj][m][n] = __builtin_amdgcn_mfma_f32_16x16x32_bf16(B_[kk][bj][n], A_[kk][m], acc[AI][bj][m][n], 0, 0, 0); } while (0)
; template <class Epi, int AI>
; __device__ __forceinline__ void skinny_item(LAS unsigned char* lds, const Gemm g, const Epi& E, const Unit u, int wr, int wc, int wave, int lane) {
;     ...
; #pragma unroll 1
;     for (int k = kbeg; k < kend; k += 128) {
;         SK_LOAD(a0, b0, k);
;         SK_LOAD(a1, b1, k + 64);
;         SK_MMA(a0, b0);
;         SK_MMA(a1, b1);
	v_mfma_f32_16x16x32_bf16 v[24:27], v[190:193], v[100:103], v[24:27]
	v_mfma_f32_16x16x32_bf16 v[20:23], v[190:193], v[96:99], v[20:23]
	v_mfma_f32_16x16x32_bf16 v[8:11], v[190:193], v[138:141], v[8:11]
	v_mfma_f32_16x16x32_bf16 v[12:15], v[190:193], v[146:149], v[12:15]
	v_mfma_f32_16x16x32_bf16 v[32:35], v[158:161], v[150:153], v[32:35]
	v_mfma_f32_16x16x32_bf16 v[28:31], v[174:177], v[162:165], v[28:31]
	s_waitcnt vmcnt(16)
	v_mfma_f32_16x16x32_bf16 v[24:27], v[194:197], v[162:165], v[24:27]
	v_mfma_f32_16x16x32_bf16 v[16:19], v[174:177], v[134:137], v[16:19]
	v_mfma_f32_16x16x32_bf16 v[20:23], v[194:197], v[134:137], v[20:23]
	v_mfma_f32_16x16x32_bf16 v[4:7], v[174:177], v[142:145], v[4:7]
	v_mfma_f32_16x16x32_bf16 v[8:11], v[194:197], v[142:145], v[8:11]
	v_mfma_f32_16x16x32_bf16 v[0:3], v[174:177], v[150:153], v[0:3]
	v_mfma_f32_16x16x32_bf16 v[12:15], v[194:197], v[150:153], v[12:15]
	s_waitcnt vmcnt(13)
	v_mfma_f32_16x16x32_bf16 v[56:59], v[206:209], v[198:201], v[56:59]
	s_waitcnt vmcnt(11)
	v_mfma_f32_16x16x32_bf16 v[52:55], v[206:209], v[214:217], v[52:55]
	s_waitcnt vmcnt(9)
	v_mfma_f32_16x16x32_bf16 v[44:47], v[206:209], v[222:225], v[44:47]
	s_waitcnt vmcnt(7)
	v_mfma_f32_16x16x32_bf16 v[36:39], v[206:209], v[230:233], v[36:39]
	s_waitcnt vmcnt(5)
	v_mfma_f32_16x16x32_bf16 v[60:63], v[240:243], v[198:201], v[60:63]
	v_mfma_f32_16x16x32_bf16 v[48:51], v[240:243], v[214:217], v[48:51]
	v_mfma_f32_16x16x32_bf16 v[40:43], v[240:243], v[222:225], v[40:43]
	v_mfma_f32_16x16x32_bf16 v[32:35], v[240:243], v[230:233], v[32:35]
	s_waitcnt vmcnt(3)
	v_mfma_f32_16x16x32_bf16 v[28:31], v[248:251], v[198:201], v[28:31]
	s_waitcnt vmcnt(1)
	v_mfma_f32_16x16x32_bf16 v[24:27], v[170:173], v[198:201], v[24:27]
	v_mfma_f32_16x16x32_bf16 v[16:19], v[248:251], v[214:217], v[16:19]
	v_mfma_f32_16x16x32_bf16 v[20:23], v[170:173], v[214:217], v[20:23]
	v_mfma_f32_16x16x32_bf16 v[4:7], v[248:251], v[222:225], v[4:7]
	v_mfma_f32_16x16x32_bf16 v[8:11], v[170:173], v[222:225], v[8:11]
	v_mfma_f32_16x16x32_bf16 v[0:3], v[248:251], v[230:233], v[0:3]
	v_mfma_f32_16x16x32_bf16 v[12:15], v[170:173], v[230:233], v[12:15]
	v_mfma_f32_16x16x32_bf16 v[56:59], v[210:213], v[202:205], v[56:59]
	v_mfma_f32_16x16x32_bf16 v[60:63], v[244:247], v[202:205], v[60:63]
	v_mfma_f32_16x16x32_bf16 v[52:55], v[210:213], v[218:221], v[52:55]
	v_mfma_f32_16x16x32_bf16 v[48:51], v[244:247], v[218:221], v[48:51]
	v_mfma_f32_16x16x32_bf16 v[44:47], v[210:213], v[226:229], v[44:47]
	v_mfma_f32_16x16x32_bf16 v[40:43], v[244:247], v[226:229], v[40:43]
	v_mfma_f32_16x16x32_bf16 v[36:39], v[210:213], v[234:237], v[36:39]
	v_mfma_f32_16x16x32_bf16 v[32:35], v[244:247], v[234:237], v[32:35]
	v_mfma_f32_16x16x32_bf16 v[28:31], v[154:157], v[202:205], v[28:31]
	s_waitcnt vmcnt(0)
	v_mfma_f32_16x16x32_bf16 v[24:27], v[92:95], v[202:205], v[24:27]
	v_mfma_f32_16x16x32_bf16 v[16:19], v[154:157], v[218:221], v[16:19]
	v_mfma_f32_16x16x32_bf16 v[20:23], v[92:95], v[218:221], v[20:23]
	v_mfma_f32_16x16x32_bf16 v[4:7], v[154:157], v[226:229], v[4:7]
	v_mfma_f32_16x16x32_bf16 v[8:11], v[92:95], v[226:229], v[8:11]
	v_mfma_f32_16x16x32_bf16 v[0:3], v[154:157], v[234:237], v[0:3]
	v_mfma_f32_16x16x32_bf16 v[12:15], v[92:95], v[234:237], v[12:15]
	s_cbranch_scc1 .LBB0_1366
	s_branch .LBB0_1368
